# layer 1 M1/M2 rebalance the other way: 320 (was 384) of the 512 mixer-A units dealt after the M2 queue; on comb15
# baseline (speedup 1.0000x reference)
; __device__ __forceinline__ float wave_sum(float v) { v = row16_sum(v); return (rlf(v, 0) + rlf(v, 16)) + (rlf(v, 32) + rlf(v, 48)); }
; __device__ __forceinline__ void mixA_unit(const Ctx& c, int l, int a) {
;     ...
;     for (int half = 0; half < 2; ++half) {
;         u32x4 raw[8][2];
; #pragma unroll
;         for (int i = 0; i < 8; ++i) { const bf16* row = VA + (size_t)(wave * 16 + half * 8 + i) * 1024; raw[i][0] = *(const u32x4*)(row + lane * 8); raw[i][1] = *(const u32x4*)(row + 512 + lane * 8); }
; #pragma unroll
;         for (int i = 0; i < 8; ++i) {
;             float x[8], y[8]; unpack8(raw[i][0], x); unpack8(raw[i][1], y);
;             float sm = 0.f, sq = 0.f;
; #pragma unroll
;             for (int e = 0; e < 8; ++e) { sm += x[e] + y[e]; sq += x[e] * x[e] + y[e] * y[e]; }
;             sm = wave_sum(sm); sq = wave_sum(sq);
;             const float mu = sm * (1.0f / 1024.0f), var = fmaxf(sq * (1.0f / 1024.0f) - mu * mu, 0.f);
;             if (lane == 0) { st_mean[wave * 16 + half * 8 + i] = mu; st_rstd[wave * 16 + half * 8 + i] = rsqrtf(var + 1e-6f); }
;         }
; __device__ __forceinline__ void m1_dispatch(const Ctx& c, int l, int u) {
;     if (u < M1_NX) { if (u < 8) mixA_sample(c, l, u); else mixB_prep(c, l, u - 8); return; }
;     u -= M1_NX;
;     if (u < M1_NI) { dsa_index_unit(c, l, u & 3, 63 - (u >> 2)); return; }
;     u -= M1_NI;
;     if (u < M1_NS) { ssc_unit(c, l, u >> 4, u & 15); return; }
;     u -= M1_NS;
;     if (u < M1_ND) {
;         dprep_unit(c, l, u >> 8, (u >> 3) & 31, u & 7); __syncthreads(); dprep_unit(c, l, u >> 8, (u >> 3) & 31, (u & 7) + 8);
;     }
;     else mixA_unit(c, l, u - M1_ND);
; }
; __device__ __forceinline__ void phase_M1(Ctx& c, int l, int q, const XcdBarrier& bar) {
;     for (;;) {
;         const int u = next_unit(c, q);
;         if (u >= M1_TOTAL) break;
;         m1_dispatch(c, l, u);
.LBB0_2562:
	s_or_b64 exec, exec, s[0:1]
	s_waitcnt lgkmcnt(0)
	s_barrier
	ds_read_b32 v0, v136
	s_mov_b64 s[0:1], -1
	s_waitcnt lgkmcnt(0)
	v_readfirstlane_b32 s18, v0
	v_readlane_b32 s44, v255, 62
	s_nop 3
	s_mul_i32 s45, s44, 0x650
	s_add_i32 s18, s18, s45
	s_mul_i32 s45, s44, 0x140
	s_addk_i32 s45, 0x64f
	s_cmp_gt_i32 s18, s45
	s_cbranch_scc1 .LBB0_2557
	s_cmp_gt_i32 s18, 15
	s_cbranch_scc0 .LBB0_2647
	s_cmpk_gt_u32 s18, 0x10f
	s_cbranch_scc0 .LBB0_2626
	s_cmpk_gt_u32 s18, 0x18f
	s_cbranch_scc0 .LBB0_2613
	s_cmpk_gt_u32 s18, 0x58f
	s_cbranch_scc0 .LBB0_2609
	s_lshl_b32 s0, s18, 4
	s_addk_i32 s0, 0x700
	s_and_b32 s10, s0, 0x1f80
	v_readlane_b32 s0, v251, 63
	v_mov_b32_e32 v60, v17
	v_lshlrev_b32_e32 v58, 3, v66
	v_mov_b32_e32 v63, s0
	v_readlane_b32 s0, v252, 0
	v_ashrrev_i32_e32 v59, 31, v58
	v_lshlrev_b64 v[68:69], 1, v[58:59]
	v_mov_b32_e32 v61, s0
	v_readlane_b32 s0, v252, 1
	v_readlane_b32 s2, v251, 40
	v_cmp_eq_u32_e32 vcc, 0, v66
	v_mov_b32_e32 v65, s0
	s_load_dwordx2 s[4:5], s[90:91], 0xc0
	s_lshl_b32 s0, s10, 11
	v_readlane_b32 s3, v251, 41
	s_waitcnt lgkmcnt(0)
	s_add_u32 s0, s4, s0
	s_addc_u32 s1, s5, 0
	s_add_u32 s6, s0, 0x24700000
	s_addc_u32 s7, s1, 0
	v_readlane_b32 s0, v250, 44
	v_readlane_b32 s1, v250, 45
	s_add_u32 s0, s6, s0
	s_addc_u32 s1, s7, s1
	v_lshl_add_u64 v[0:1], s[0:1], 0, v[68:69]
	global_load_dwordx4 v[70:73], v[0:1], off
	global_load_dwordx4 v[74:77], v[0:1], off offset:1024
	v_readlane_b32 s0, v250, 46
	v_readlane_b32 s1, v250, 47
	s_add_u32 s0, s6, s0
	s_addc_u32 s1, s7, s1
	v_lshl_add_u64 v[0:1], s[0:1], 0, v[68:69]
	v_readlane_b32 s0, v250, 48
	v_readlane_b32 s1, v250, 49
	s_add_u32 s0, s6, s0
	s_addc_u32 s1, s7, s1
	global_load_dwordx4 v[54:57], v[0:1], off
	global_load_dwordx4 v[50:53], v[0:1], off offset:1024
	v_lshl_add_u64 v[0:1], s[0:1], 0, v[68:69]
	v_readlane_b32 s0, v250, 50
	v_readlane_b32 s1, v250, 51
	s_add_u32 s0, s6, s0
	s_addc_u32 s1, s7, s1
	global_load_dwordx4 v[46:49], v[0:1], off
	global_load_dwordx4 v[42:45], v[0:1], off offset:1024
	v_lshl_add_u64 v[0:1], s[0:1], 0, v[68:69]
	v_readlane_b32 s0, v250, 52
	v_readlane_b32 s1, v250, 53
	s_add_u32 s0, s6, s0
	s_addc_u32 s1, s7, s1
	global_load_dwordx4 v[38:41], v[0:1], off
	global_load_dwordx4 v[34:37], v[0:1], off offset:1024
	v_lshl_add_u64 v[0:1], s[0:1], 0, v[68:69]
	v_readlane_b32 s0, v250, 54
	v_readlane_b32 s1, v250, 55
	s_add_u32 s0, s6, s0
	s_addc_u32 s1, s7, s1
	global_load_dwordx4 v[30:33], v[0:1], off
	global_load_dwordx4 v[26:29], v[0:1], off offset:1024
	v_lshl_add_u64 v[0:1], s[0:1], 0, v[68:69]
	v_readlane_b32 s0, v250, 56
	v_readlane_b32 s1, v250, 57
	s_add_u32 s0, s6, s0
	s_addc_u32 s1, s7, s1
	global_load_dwordx4 v[22:25], v[0:1], off
	global_load_dwordx4 v[18:21], v[0:1], off offset:1024
	v_lshl_add_u64 v[0:1], s[0:1], 0, v[68:69]
	v_readlane_b32 s0, v250, 58
	v_readlane_b32 s1, v250, 59
	s_add_u32 s0, s6, s0
	s_addc_u32 s1, s7, s1
	global_load_dwordx4 v[12:15], v[0:1], off
	global_load_dwordx4 v[8:11], v[0:1], off offset:1024
	v_lshl_add_u64 v[0:1], s[0:1], 0, v[68:69]
	global_load_dwordx4 v[4:7], v[0:1], off
	s_nop 0
	global_load_dwordx4 v[0:3], v[0:1], off offset:1024
	s_waitcnt vmcnt(15)
	v_lshlrev_b32_e32 v16, 16, v70
	s_waitcnt vmcnt(14)
	v_lshlrev_b32_e32 v79, 16, v74
	v_and_b32_e32 v59, 0xffff0000, v70
	v_and_b32_e32 v74, 0xffff0000, v74
	v_add_f32_e32 v83, v16, v79
	v_mul_f32_e32 v79, v79, v79
	v_fmac_f32_e32 v79, v16, v16
	v_add_f32_e32 v16, v59, v74
	v_mul_f32_e32 v74, v74, v74
	v_lshlrev_b32_e32 v67, 16, v71
	v_lshlrev_b32_e32 v80, 16, v75
	v_add_f32_e32 v83, 0, v83
	v_fmac_f32_e32 v74, v59, v59
	v_add_f32_e32 v16, v16, v83
	v_add_f32_e32 v59, v79, v74
	v_add_f32_e32 v74, v67, v80
	v_and_b32_e32 v70, 0xffff0000, v71
	v_and_b32_e32 v75, 0xffff0000, v75
	v_add_f32_e32 v16, v74, v16
	v_mul_f32_e32 v74, v80, v80
	v_fmac_f32_e32 v74, v67, v67
	v_add_f32_e32 v67, v70, v75
	v_add_f32_e32 v16, v67, v16
	v_mul_f32_e32 v67, v75, v75
	v_lshlrev_b32_e32 v71, 16, v72
	v_lshlrev_b32_e32 v81, 16, v76
	v_add_f32_e32 v59, v74, v59
	v_fmac_f32_e32 v67, v70, v70
	v_add_f32_e32 v59, v67, v59
	v_add_f32_e32 v67, v71, v81
	v_add_f32_e32 v16, v67, v16
	v_mul_f32_e32 v67, v81, v81
	v_and_b32_e32 v72, 0xffff0000, v72
	v_and_b32_e32 v76, 0xffff0000, v76
	v_fmac_f32_e32 v67, v71, v71
	v_add_f32_e32 v59, v67, v59
	v_add_f32_e32 v67, v72, v76
	v_add_f32_e32 v16, v67, v16
	v_mul_f32_e32 v67, v76, v76
	v_lshlrev_b32_e32 v78, 16, v73
	v_lshlrev_b32_e32 v82, 16, v77
	v_fmac_f32_e32 v67, v72, v72
	v_add_f32_e32 v59, v67, v59
	v_add_f32_e32 v67, v78, v82
	v_add_f32_e32 v16, v67, v16
	v_mul_f32_e32 v67, v82, v82
	v_and_b32_e32 v73, 0xffff0000, v73
	v_and_b32_e32 v77, 0xffff0000, v77
	v_fmac_f32_e32 v67, v78, v78
	v_add_f32_e32 v59, v67, v59
	v_add_f32_e32 v67, v73, v77
	v_add_f32_e32 v16, v67, v16
	v_mul_f32_e32 v67, v77, v77
	v_fmac_f32_e32 v67, v73, v73
	v_add_f32_dpp v16, v16, v16 quad_perm:[1,0,3,2] row_mask:0xf bank_mask:0xf bound_ctrl:1
	v_add_f32_e32 v59, v67, v59
	s_nop 0
	v_add_f32_dpp v16, v16, v16 quad_perm:[2,3,0,1] row_mask:0xf bank_mask:0xf bound_ctrl:1
	s_nop 1
	v_add_f32_dpp v16, v16, v16 row_half_mirror row_mask:0xf bank_mask:0xf bound_ctrl:1
	s_nop 1
	v_add_f32_dpp v16, v16, v16 row_mirror row_mask:0xf bank_mask:0xf bound_ctrl:1
	s_nop 0
	v_readlane_b32 s9, v16, 0
	v_readlane_b32 s12, v16, 16
	v_readlane_b32 s1, v16, 32
	v_readlane_b32 s11, v16, 48
	v_add_f32_dpp v16, v59, v59 quad_perm:[1,0,3,2] row_mask:0xf bank_mask:0xf bound_ctrl:1
	s_nop 1
	v_add_f32_dpp v16, v16, v16 quad_perm:[2,3,0,1] row_mask:0xf bank_mask:0xf bound_ctrl:1
	s_nop 1
	v_add_f32_dpp v16, v16, v16 row_half_mirror row_mask:0xf bank_mask:0xf bound_ctrl:1
	s_nop 1
	v_add_f32_dpp v16, v16, v16 row_mirror row_mask:0xf bank_mask:0xf bound_ctrl:1
	s_nop 0
	v_readlane_b32 s8, v16, 0
	v_readlane_b32 s14, v16, 16
	v_readlane_b32 s0, v16, 32
	v_readlane_b32 s13, v16, 48
	v_lshl_add_u32 v16, s2, 2, v65
	s_and_saveexec_b64 s[2:3], vcc
	s_cbranch_execz .LBB0_2569
	v_mov_b32_e32 v70, s14
	v_mov_b32_e32 v71, s12
	v_mov_b32_e32 v72, s13
	v_mov_b32_e32 v73, s11
	v_pk_add_f32 v[70:71], s[8:9], v[70:71]
	v_pk_add_f32 v[72:73], s[0:1], v[72:73]
	s_mov_b32 s0, 0x3a800000
	v_pk_add_f32 v[70:71], v[70:71], v[72:73]
	s_nop 0
	v_pk_mul_f32 v[70:71], v[70:71], s[0:1] op_sel_hi:[1,0]
	s_nop 0
	v_fma_f32 v59, -v71, v71, v70
	v_max_f32_e32 v59, 0, v59
	v_add_f32_e32 v59, 0x358637bd, v59
	v_mul_f32_e32 v67, 0x4b800000, v59
	v_cmp_gt_f32_e64 s[0:1], s40, v59
	s_nop 1
	v_cndmask_b32_e64 v59, v59, v67, s[0:1]
	v_rsq_f32_e32 v59, v59
	s_nop 0
	v_mul_f32_e32 v67, 0x45800000, v59
	v_cndmask_b32_e64 v59, v59, v67, s[0:1]
	ds_write2st64_b32 v16, v71, v59 offset1:2
